# indexer scoring loop: next chunk's LDS staging write and global prefetch issued right behind the MFMAs; end-of-iteration wait covers only the staging write
# speedup vs baseline: 1.0026x; 1.0002x over previous
.Lidx_loop:
	v_add_u32_e32 v76, s11, v73
	ds_read_b128 v[118:121], v76
	ds_read_b128 v[126:129], v76 offset:4608
	ds_read_b128 v[114:117], v76 offset:32
	ds_read_b128 v[122:125], v76 offset:4640
	ds_read_b128 v[110:113], v76 offset:64
	ds_read_b128 v[106:109], v76 offset:4672
	ds_read_b128 v[86:89], v76 offset:4704
	ds_read_b128 v[102:105], v76 offset:96
	s_waitcnt lgkmcnt(6)
	v_mfma_f32_32x32x16_bf16 v[18:33], v[34:37], v[118:121], 0
	v_mfma_f32_32x32x16_bf16 v[2:17], v[34:37], v[126:129], 0
	s_waitcnt lgkmcnt(4)
	v_mfma_f32_32x32x16_bf16 v[18:33], v[38:41], v[114:117], v[18:33]
	v_mfma_f32_32x32x16_bf16 v[2:17], v[38:41], v[122:125], v[2:17]
	s_waitcnt lgkmcnt(2)
	v_mfma_f32_32x32x16_bf16 v[18:33], v[42:45], v[110:113], v[18:33]
	v_mfma_f32_32x32x16_bf16 v[2:17], v[42:45], v[106:109], v[2:17]
	s_waitcnt lgkmcnt(0)
	v_mfma_f32_32x32x16_bf16 v[2:17], v[46:49], v[86:89], v[2:17]
	v_mfma_f32_32x32x16_bf16 v[18:33], v[46:49], v[102:105], v[18:33]
	s_add_i32 s0, s2, 1
	s_cmp_ge_u32 s0, s8
	s_cbranch_scc1 .Lidx_nost
	s_xor_b32 s11, s11, 0x2400
	s_waitcnt vmcnt(0)
	v_add_u32_e32 v76, s11, v72
	ds_write_b128 v76, v[66:69]
	s_add_i32 s0, s2, 2
	s_cmp_ge_u32 s0, s8
	s_cbranch_scc1 .Lidx_nost
	global_load_dwordx4 v[66:69], v[70:71], off
	v_lshl_add_u64 v[70:71], v[70:71], 0, s[12:13]
.Lidx_nost:
	s_nop 10
	v_max_i32_e32 v2, 0, v2
	v_max_i32_e32 v3, 0, v3
	v_max_i32_e32 v4, 0, v4
	v_max_i32_e32 v5, 0, v5
	v_max_i32_e32 v6, 0, v6
	v_max_i32_e32 v7, 0, v7
	v_max_i32_e32 v8, 0, v8
	v_max_i32_e32 v9, 0, v9
	v_max_i32_e32 v10, 0, v10
	v_max_i32_e32 v11, 0, v11
	v_max_i32_e32 v12, 0, v12
	v_max_i32_e32 v13, 0, v13
	v_max_i32_e32 v14, 0, v14
	v_max_i32_e32 v15, 0, v15
	v_max_i32_e32 v16, 0, v16
	v_max_i32_e32 v17, 0, v17
	v_max_i32_e32 v18, 0, v18
	v_max_i32_e32 v19, 0, v19
	v_max_i32_e32 v20, 0, v20
	v_max_i32_e32 v21, 0, v21
	v_max_i32_e32 v22, 0, v22
	v_max_i32_e32 v23, 0, v23
	v_max_i32_e32 v24, 0, v24
	v_max_i32_e32 v25, 0, v25
	v_max_i32_e32 v26, 0, v26
	v_max_i32_e32 v27, 0, v27
	v_max_i32_e32 v28, 0, v28
	v_max_i32_e32 v29, 0, v29
	v_max_i32_e32 v30, 0, v30
	v_max_i32_e32 v31, 0, v31
	v_max_i32_e32 v32, 0, v32
	v_max_i32_e32 v33, 0, v33
	v_pk_mul_f32 v[78:79], v[50:51], v[2:3]
	v_pk_mul_f32 v[80:81], v[58:59], v[10:11]
	v_pk_mul_f32 v[82:83], v[50:51], v[18:19]
	v_pk_mul_f32 v[84:85], v[58:59], v[26:27]
	v_pk_fma_f32 v[78:79], v[52:53], v[4:5], v[78:79]
	v_pk_fma_f32 v[80:81], v[60:61], v[12:13], v[80:81]
	v_pk_fma_f32 v[82:83], v[52:53], v[20:21], v[82:83]
	v_pk_fma_f32 v[84:85], v[60:61], v[28:29], v[84:85]
	v_pk_fma_f32 v[78:79], v[54:55], v[6:7], v[78:79]
	v_pk_fma_f32 v[80:81], v[62:63], v[14:15], v[80:81]
	v_pk_fma_f32 v[82:83], v[54:55], v[22:23], v[82:83]
	v_pk_fma_f32 v[84:85], v[62:63], v[30:31], v[84:85]
	v_pk_fma_f32 v[78:79], v[56:57], v[8:9], v[78:79]
	v_pk_fma_f32 v[80:81], v[64:65], v[16:17], v[80:81]
	v_pk_fma_f32 v[82:83], v[56:57], v[24:25], v[82:83]
	v_pk_fma_f32 v[84:85], v[64:65], v[32:33], v[84:85]
	v_add_f32_e32 v2, v78, v79
	v_add_f32_e32 v10, v80, v81
	v_add_f32_e32 v18, v82, v83
	v_add_f32_e32 v26, v84, v85
	s_nop 1
	v_permlane32_swap_b32_e32 v18, v26
	v_permlane32_swap_b32_e32 v2, v10
	v_add_f32_e32 v18, v18, v26
	v_add_f32_e32 v2, v2, v10
	ds_write2_b32 v251, v18, v2 offset1:32
	v_add_u32_e32 v251, 0x100, v251
	s_add_i32 s2, s2, 1
	s_cmp_ge_u32 s2, s8
	s_cbranch_scc1 .Lidx_done
	s_waitcnt lgkmcnt(1)
	s_barrier
	s_branch .Lidx_loop
